# GEMM K-loops: s_setprio pairs removed as well (on top of v57)
# baseline (speedup 1.0000x reference)
; #define PG8_STAGE(bufoff, gbase, voff) do { _Pragma("unroll") for (int _i = 0; _i < 2; ++_i) \
;         __builtin_amdgcn_global_load_lds((const unsigned*)((const char*)(gbase) + (voff)[_i]), (PG8_LAS unsigned*)(lds + (bufoff) + ldsw + _i * 8192), 16, 0, 0); } while (0)
; #define PG8_LDA(dst, b, h) do { _Pragma("unroll") for (int m = 0; m < 4; ++m) _Pragma("unroll") for (int k = 0; k < 2; ++k) dst[m][k] = *(const PG8_LAS bf16x8*)(lds + PG8_SA(b, h) + aoff + m * 2048 + k * 1024); } while (0)
; #define PG8_LDB(dst, b, h) do { _Pragma("unroll") for (int n = 0; n < 2; ++n) _Pragma("unroll") for (int k = 0; k < 2; ++k) dst[n][k] = *(const PG8_LAS bf16x8*)(lds + PG8_SB(b, h) + boff + n * 2048 + k * 1024); } while (0)
; #define PG8_MMA(ai, bj, At, Bt) do { __builtin_amdgcn_s_setprio(1); _Pragma("unroll") for (int m = 0; m < 4; ++m) _Pragma("unroll") for (int n = 0; n < 2; ++n) _Pragma("unroll") for (int k = 0; k < 2; ++k) \
;         acc[ai][bj][m][n] = __builtin_amdgcn_mfma_f32_16x16x32_bf16(Bt[n][k], At[m][k], acc[ai][bj][m][n], 0, 0, 0); __builtin_amdgcn_s_setprio(0); } while (0)
; #define PG8_WAIT_V(n) asm volatile("s_waitcnt vmcnt(" #n ")" ::: "memory")
; #define PG8_WAIT_L(n) asm volatile("s_waitcnt lgkmcnt(" #n ")" ::: "memory")
; template <class Epi, class Sched, bool ALIGN_EPI = false, bool SP2 = false>
; __device__ __forceinline__ void gemm_phase(PG8_LAS unsigned char* lds, const Gemm g, const Sched& S, const Epi& E) {
;     ...
;             const bool last = (t == nt - 2);
;             const char* a1 = cA + (size_t)(t + 1) * kstep;
;             const char* a2 = last ? nA : cA + (size_t)(t + 2) * kstep; const char* b2 = last ? nB : cB + (size_t)(t + 2) * kstep;
;             const char* a3 = a2 + kstep; const char* b3 = b2 + kstep;
;             if (last && has_next) S.a_ready(nxt);
;             if constexpr (SP2) {
;             PG8_LDB(B0, 0, 0); PG8_LDB(B1, 0, 1); PG8_SCHED; PG8_LDA(At, 0, 0); PG8_STAGE(PG8_SA(1, 1), a1 + hstep, voffA);
;             PG8_WAIT_V(8); PG8_WAIT_L(0); PG8_BAR; PG8_MMA(0, 0, At, B0); PG8_MMA(0, 1, At, B1); PG8_BAR; PG8_SCHED;
;             PG8_LDA(At, 0, 1); PG8_STAGE(PG8_SB(0, 0), b2, voffB); PG8_STAGE(PG8_SB(0, 1), b2 + hstep, voffB); PG8_STAGE(PG8_SA(0, 0), a2, voffA);
;             PG8_WAIT_V(8); PG8_WAIT_L(0); PG8_BAR; PG8_MMA(1, 0, At, B0); PG8_MMA(1, 1, At, B1); PG8_BAR; PG8_SCHED;
.LBB0_114:
	s_add_u32 s20, s8, 0xfffc0080
	s_addc_u32 s21, s9, -1
	s_add_i32 s41, 0, 0x10000
	s_cmp_eq_u32 s40, 12
	s_cselect_b32 s35, s13, s21
	s_cselect_b32 s34, s22, s20
	v_add_u32_e32 v0, s41, v154
	s_cselect_b32 s31, s11, s39
	s_cselect_b32 s30, s23, s38
	s_add_i32 s20, 0, 0x14000
	ds_read_b128 v[158:161], v0
	ds_read_b128 v[162:165], v0 offset:1024
	ds_read_b128 v[166:169], v0 offset:2048
	ds_read_b128 v[170:173], v0 offset:3072
	v_add_u32_e32 v0, s20, v154
	ds_read_b128 v[174:177], v0
	ds_read_b128 v[178:181], v0 offset:1024
	ds_read_b128 v[182:185], v0 offset:2048
	ds_read_b128 v[186:189], v0 offset:3072
	s_add_i32 m0, s46, 0xc000
	ds_read_b128 v[190:193], v156
	ds_read_b128 v[194:197], v156 offset:1024
	ds_read_b128 v[206:209], v156 offset:2048
	ds_read_b128 v[210:213], v156 offset:3072
	ds_read_b128 v[214:217], v156 offset:4096
	ds_read_b128 v[218:221], v156 offset:5120
	ds_read_b128 v[222:225], v156 offset:6144
	ds_read_b128 v[226:229], v156 offset:7168
	global_load_lds_dwordx4 v146, s[8:9]
	s_add_i32 m0, s46, 0xe000
	s_nop 0
	global_load_lds_dwordx4 v148, s[8:9]
	s_waitcnt vmcnt(8)
	s_waitcnt lgkmcnt(0)
	s_barrier
	v_mfma_f32_16x16x32_bf16 v[126:129], v[158:161], v[190:193], v[126:129]
	v_mfma_f32_16x16x32_bf16 v[122:125], v[166:169], v[190:193], v[122:125]
	v_mfma_f32_16x16x32_bf16 v[114:117], v[158:161], v[206:209], v[114:117]
	v_mfma_f32_16x16x32_bf16 v[106:109], v[166:169], v[206:209], v[106:109]
	v_mfma_f32_16x16x32_bf16 v[98:101], v[158:161], v[214:217], v[98:101]
	v_mfma_f32_16x16x32_bf16 v[90:93], v[166:169], v[214:217], v[90:93]
	v_mfma_f32_16x16x32_bf16 v[82:85], v[158:161], v[222:225], v[82:85]
	v_mfma_f32_16x16x32_bf16 v[74:77], v[166:169], v[222:225], v[74:77]
	v_mfma_f32_16x16x32_bf16 v[126:129], v[162:165], v[194:197], v[126:129]
	v_mfma_f32_16x16x32_bf16 v[122:125], v[170:173], v[194:197], v[122:125]
	v_mfma_f32_16x16x32_bf16 v[114:117], v[162:165], v[210:213], v[114:117]
	v_mfma_f32_16x16x32_bf16 v[106:109], v[170:173], v[210:213], v[106:109]
	v_mfma_f32_16x16x32_bf16 v[98:101], v[162:165], v[218:221], v[98:101]
	v_mfma_f32_16x16x32_bf16 v[90:93], v[170:173], v[218:221], v[90:93]
	v_mfma_f32_16x16x32_bf16 v[82:85], v[162:165], v[226:229], v[82:85]
	v_mfma_f32_16x16x32_bf16 v[74:77], v[170:173], v[226:229], v[74:77]
	v_mfma_f32_16x16x32_bf16 v[118:121], v[174:177], v[190:193], v[118:121]
	v_mfma_f32_16x16x32_bf16 v[110:113], v[182:185], v[190:193], v[110:113]
	v_mfma_f32_16x16x32_bf16 v[102:105], v[174:177], v[206:209], v[102:105]
	v_mfma_f32_16x16x32_bf16 v[94:97], v[182:185], v[206:209], v[94:97]
	v_mfma_f32_16x16x32_bf16 v[86:89], v[174:177], v[214:217], v[86:89]
	v_mfma_f32_16x16x32_bf16 v[78:81], v[182:185], v[214:217], v[78:81]
	v_mfma_f32_16x16x32_bf16 v[70:73], v[174:177], v[222:225], v[70:73]
	v_mfma_f32_16x16x32_bf16 v[66:69], v[182:185], v[222:225], v[66:69]
	v_mfma_f32_16x16x32_bf16 v[118:121], v[178:181], v[194:197], v[118:121]
	v_mfma_f32_16x16x32_bf16 v[110:113], v[186:189], v[194:197], v[110:113]
	v_mfma_f32_16x16x32_bf16 v[102:105], v[178:181], v[210:213], v[102:105]
	v_mfma_f32_16x16x32_bf16 v[94:97], v[186:189], v[210:213], v[94:97]
	v_mfma_f32_16x16x32_bf16 v[86:89], v[178:181], v[218:221], v[86:89]
	v_mfma_f32_16x16x32_bf16 v[78:81], v[186:189], v[218:221], v[78:81]
	v_mfma_f32_16x16x32_bf16 v[70:73], v[178:181], v[226:229], v[70:73]
	v_mfma_f32_16x16x32_bf16 v[66:69], v[186:189], v[226:229], v[66:69]
	s_barrier
	s_add_i32 s21, s41, s29
	s_mov_b32 m0, s21
	ds_read_b128 v[190:193], v156 offset:16384
	ds_read_b128 v[194:197], v156 offset:17408
	ds_read_b128 v[206:209], v156 offset:18432
	ds_read_b128 v[210:213], v156 offset:19456
	ds_read_b128 v[214:217], v156 offset:20480
	ds_read_b128 v[218:221], v156 offset:21504
	ds_read_b128 v[222:225], v156 offset:22528
	ds_read_b128 v[226:229], v156 offset:23552
	global_load_lds_dwordx4 v134, s[30:31]
	s_add_i32 m0, s21, 0x2000
	s_add_u32 s82, s30, 0x40000
	s_addc_u32 s83, s31, 0
	s_add_i32 s20, s20, s29
	global_load_lds_dwordx4 v130, s[30:31]
	s_mov_b32 m0, s20
	s_nop 0
	global_load_lds_dwordx4 v134, s[82:83]
	s_add_i32 m0, s20, 0x2000
	s_nop 0
	global_load_lds_dwordx4 v130, s[82:83]
	s_mov_b32 m0, s46
	s_nop 0
	global_load_lds_dwordx4 v136, s[34:35]
	s_mov_b32 m0, s47
	s_nop 0
	global_load_lds_dwordx4 v132, s[34:35]
	s_waitcnt vmcnt(8)
	s_waitcnt lgkmcnt(0)
	s_barrier
	v_mfma_f32_16x16x32_bf16 v[62:65], v[158:161], v[190:193], v[62:65]
	v_mfma_f32_16x16x32_bf16 v[58:61], v[166:169], v[190:193], v[58:61]
	v_mfma_f32_16x16x32_bf16 v[50:53], v[158:161], v[206:209], v[50:53]
	v_mfma_f32_16x16x32_bf16 v[42:45], v[166:169], v[206:209], v[42:45]
	v_mfma_f32_16x16x32_bf16 v[34:37], v[158:161], v[214:217], v[34:37]
	v_mfma_f32_16x16x32_bf16 v[26:29], v[166:169], v[214:217], v[26:29]
	v_mfma_f32_16x16x32_bf16 v[18:21], v[158:161], v[222:225], v[18:21]
	v_mfma_f32_16x16x32_bf16 v[10:13], v[166:169], v[222:225], v[10:13]
	v_mfma_f32_16x16x32_bf16 v[62:65], v[162:165], v[194:197], v[62:65]
	v_mfma_f32_16x16x32_bf16 v[58:61], v[170:173], v[194:197], v[58:61]
	v_mfma_f32_16x16x32_bf16 v[50:53], v[162:165], v[210:213], v[50:53]
	v_mfma_f32_16x16x32_bf16 v[42:45], v[170:173], v[210:213], v[42:45]
	v_mfma_f32_16x16x32_bf16 v[34:37], v[162:165], v[218:221], v[34:37]
	v_mfma_f32_16x16x32_bf16 v[26:29], v[170:173], v[218:221], v[26:29]
	v_mfma_f32_16x16x32_bf16 v[18:21], v[162:165], v[226:229], v[18:21]
	v_mfma_f32_16x16x32_bf16 v[10:13], v[170:173], v[226:229], v[10:13]
	v_mfma_f32_16x16x32_bf16 v[54:57], v[174:177], v[190:193], v[54:57]
	v_mfma_f32_16x16x32_bf16 v[46:49], v[182:185], v[190:193], v[46:49]
	v_mfma_f32_16x16x32_bf16 v[38:41], v[174:177], v[206:209], v[38:41]
	v_mfma_f32_16x16x32_bf16 v[30:33], v[182:185], v[206:209], v[30:33]
	v_mfma_f32_16x16x32_bf16 v[22:25], v[174:177], v[214:217], v[22:25]
	v_mfma_f32_16x16x32_bf16 v[14:17], v[182:185], v[214:217], v[14:17]
	v_mfma_f32_16x16x32_bf16 v[6:9], v[174:177], v[222:225], v[6:9]
	v_mfma_f32_16x16x32_bf16 v[2:5], v[182:185], v[222:225], v[2:5]
	v_mfma_f32_16x16x32_bf16 v[54:57], v[178:181], v[194:197], v[54:57]
	v_mfma_f32_16x16x32_bf16 v[46:49], v[186:189], v[194:197], v[46:49]
	v_mfma_f32_16x16x32_bf16 v[38:41], v[178:181], v[210:213], v[38:41]
	v_mfma_f32_16x16x32_bf16 v[30:33], v[186:189], v[210:213], v[30:33]
	v_mfma_f32_16x16x32_bf16 v[22:25], v[178:181], v[218:221], v[22:25]
	v_mfma_f32_16x16x32_bf16 v[14:17], v[186:189], v[218:221], v[14:17]
	v_mfma_f32_16x16x32_bf16 v[6:9], v[178:181], v[226:229], v[6:9]
	v_mfma_f32_16x16x32_bf16 v[2:5], v[186:189], v[226:229], v[2:5]
	s_barrier
; #define PG8_STAGE(bufoff, gbase, voff) do { _Pragma("unroll") for (int _i = 0; _i < 2; ++_i) \
;         __builtin_amdgcn_global_load_lds((const unsigned*)((const char*)(gbase) + (voff)[_i]), (PG8_LAS unsigned*)(lds + (bufoff) + ldsw + _i * 8192), 16, 0, 0); } while (0)
; #define PG8_LDA(dst, b, h) do { _Pragma("unroll") for (int m = 0; m < 4; ++m) _Pragma("unroll") for (int k = 0; k < 2; ++k) dst[m][k] = *(const PG8_LAS bf16x8*)(lds + PG8_SA(b, h) + aoff + m * 2048 + k * 1024); } while (0)
; #define PG8_LDB(dst, b, h) do { _Pragma("unroll") for (int n = 0; n < 2; ++n) _Pragma("unroll") for (int k = 0; k < 2; ++k) dst[n][k] = *(const PG8_LAS bf16x8*)(lds + PG8_SB(b, h) + boff + n * 2048 + k * 1024); } while (0)
; #define PG8_MMA(ai, bj, At, Bt) do { __builtin_amdgcn_s_setprio(1); _Pragma("unroll") for (int m = 0; m < 4; ++m) _Pragma("unroll") for (int n = 0; n < 2; ++n) _Pragma("unroll") for (int k = 0; k < 2; ++k) \
;         acc[ai][bj][m][n] = __builtin_amdgcn_mfma_f32_16x16x32_bf16(Bt[n][k], At[m][k], acc[ai][bj][m][n], 0, 0, 0); __builtin_amdgcn_s_setprio(0); } while (0)
; #define PG8_WAIT_V(n) asm volatile("s_waitcnt vmcnt(" #n ")" ::: "memory")
; #define PG8_WAIT_L(n) asm volatile("s_waitcnt lgkmcnt(" #n ")" ::: "memory")
; #define PG8_BAR __builtin_amdgcn_s_barrier()
; #define PG8_SCHED __builtin_amdgcn_sched_barrier(0)
; template <class Epi, class Sched, bool ALIGN_EPI = false, bool SP2 = false>
; __device__ __forceinline__ void gemm_phase(PG8_LAS unsigned char* lds, const Gemm g, const Sched& S, const Epi& E) {
;     ...
;             PG8_LDB(B0, 1, 0); PG8_LDB(B1, 1, 1); PG8_SCHED; PG8_LDA(At, 1, 0); PG8_STAGE(PG8_SA(0, 1), a2 + hstep, voffA);
;             PG8_WAIT_V(8); PG8_WAIT_L(0); PG8_BAR; PG8_MMA(0, 0, At, B0); PG8_MMA(0, 1, At, B1); PG8_BAR; PG8_SCHED;
;             PG8_LDA(At, 1, 1); PG8_STAGE(PG8_SB(1, 0), b3, voffB); PG8_STAGE(PG8_SB(1, 1), b3 + hstep, voffB); PG8_STAGE(PG8_SA(1, 0), a3, voffA);
;             PG8_WAIT_V(8); PG8_WAIT_L(0); PG8_BAR; PG8_MMA(1, 0, At, B0); PG8_MMA(1, 1, At, B1); PG8_BAR; PG8_SCHED;
	s_add_i32 s20, 0, 0x18000
	v_add_u32_e32 v0, s20, v154
	s_add_i32 s21, 0, 0x1c000
	ds_read_b128 v[158:161], v0
	ds_read_b128 v[162:165], v0 offset:1024
	ds_read_b128 v[166:169], v0 offset:2048
	ds_read_b128 v[170:173], v0 offset:3072
	v_add_u32_e32 v0, s21, v154
	ds_read_b128 v[174:177], v0
	ds_read_b128 v[178:181], v0 offset:1024
	ds_read_b128 v[182:185], v0 offset:2048
	ds_read_b128 v[186:189], v0 offset:3072
	s_add_u32 vcc_lo, s34, 0x40000
	s_addc_u32 vcc_hi, s35, 0
	s_mov_b32 m0, s52
	ds_read_b128 v[190:193], v156 offset:32768
	ds_read_b128 v[194:197], v156 offset:33792
	ds_read_b128 v[206:209], v156 offset:34816
	ds_read_b128 v[210:213], v156 offset:35840
	ds_read_b128 v[214:217], v156 offset:36864
	ds_read_b128 v[218:221], v156 offset:37888
	ds_read_b128 v[222:225], v156 offset:38912
	ds_read_b128 v[226:229], v156 offset:39936
	global_load_lds_dwordx4 v136, vcc
	s_mov_b32 m0, s53
	s_nop 0
	global_load_lds_dwordx4 v132, vcc
	s_waitcnt vmcnt(8)
	s_waitcnt lgkmcnt(0)
	s_barrier
	v_mfma_f32_16x16x32_bf16 v[126:129], v[158:161], v[190:193], v[126:129]
	v_mfma_f32_16x16x32_bf16 v[122:125], v[166:169], v[190:193], v[122:125]
	v_mfma_f32_16x16x32_bf16 v[114:117], v[158:161], v[206:209], v[114:117]
	v_mfma_f32_16x16x32_bf16 v[106:109], v[166:169], v[206:209], v[106:109]
	v_mfma_f32_16x16x32_bf16 v[98:101], v[158:161], v[214:217], v[98:101]
	v_mfma_f32_16x16x32_bf16 v[90:93], v[166:169], v[214:217], v[90:93]
	v_mfma_f32_16x16x32_bf16 v[82:85], v[158:161], v[222:225], v[82:85]
	v_mfma_f32_16x16x32_bf16 v[74:77], v[166:169], v[222:225], v[74:77]
	v_mfma_f32_16x16x32_bf16 v[126:129], v[162:165], v[194:197], v[126:129]
	v_mfma_f32_16x16x32_bf16 v[122:125], v[170:173], v[194:197], v[122:125]
	v_mfma_f32_16x16x32_bf16 v[114:117], v[162:165], v[210:213], v[114:117]
	v_mfma_f32_16x16x32_bf16 v[106:109], v[170:173], v[210:213], v[106:109]
	v_mfma_f32_16x16x32_bf16 v[98:101], v[162:165], v[218:221], v[98:101]
	v_mfma_f32_16x16x32_bf16 v[90:93], v[170:173], v[218:221], v[90:93]
	v_mfma_f32_16x16x32_bf16 v[82:85], v[162:165], v[226:229], v[82:85]
	v_mfma_f32_16x16x32_bf16 v[74:77], v[170:173], v[226:229], v[74:77]
	v_mfma_f32_16x16x32_bf16 v[118:121], v[174:177], v[190:193], v[118:121]
	v_mfma_f32_16x16x32_bf16 v[110:113], v[182:185], v[190:193], v[110:113]
	v_mfma_f32_16x16x32_bf16 v[102:105], v[174:177], v[206:209], v[102:105]
	v_mfma_f32_16x16x32_bf16 v[94:97], v[182:185], v[206:209], v[94:97]
	v_mfma_f32_16x16x32_bf16 v[86:89], v[174:177], v[214:217], v[86:89]
	v_mfma_f32_16x16x32_bf16 v[78:81], v[182:185], v[214:217], v[78:81]
	v_mfma_f32_16x16x32_bf16 v[70:73], v[174:177], v[222:225], v[70:73]
	v_mfma_f32_16x16x32_bf16 v[66:69], v[182:185], v[222:225], v[66:69]
	v_mfma_f32_16x16x32_bf16 v[118:121], v[178:181], v[194:197], v[118:121]
	v_mfma_f32_16x16x32_bf16 v[110:113], v[186:189], v[194:197], v[110:113]
	v_mfma_f32_16x16x32_bf16 v[102:105], v[178:181], v[210:213], v[102:105]
	v_mfma_f32_16x16x32_bf16 v[94:97], v[186:189], v[210:213], v[94:97]
	v_mfma_f32_16x16x32_bf16 v[86:89], v[178:181], v[218:221], v[86:89]
	v_mfma_f32_16x16x32_bf16 v[78:81], v[186:189], v[218:221], v[78:81]
	v_mfma_f32_16x16x32_bf16 v[70:73], v[178:181], v[226:229], v[70:73]
	v_mfma_f32_16x16x32_bf16 v[66:69], v[186:189], v[226:229], v[66:69]
	s_barrier
	s_add_i32 s20, s20, s29
	s_add_i32 m0, s20, 0xffffff80
	ds_read_b128 v[190:193], v156 offset:49152
	ds_read_b128 v[194:197], v156 offset:50176
	ds_read_b128 v[206:209], v156 offset:51200
	ds_read_b128 v[210:213], v156 offset:52224
	ds_read_b128 v[214:217], v156 offset:53248
	ds_read_b128 v[218:221], v156 offset:54272
	ds_read_b128 v[222:225], v156 offset:55296
	ds_read_b128 v[226:229], v156 offset:56320
	global_load_lds_dwordx4 v134, s[30:31] offset:128
	s_add_i32 m0, s20, 0x1f80
	s_add_i32 s20, s21, s29
	global_load_lds_dwordx4 v130, s[30:31] offset:128
	s_add_u32 s30, s30, 0x40080
	s_addc_u32 s31, s31, 0
	s_mov_b32 m0, s20
	s_nop 0
	global_load_lds_dwordx4 v134, s[30:31]
	s_add_i32 m0, s20, 0x2000
	s_nop 0
	global_load_lds_dwordx4 v130, s[30:31]
	s_add_i32 m0, s55, 0xffffff80
	s_nop 0
	global_load_lds_dwordx4 v136, s[34:35] offset:128
	s_add_i32 m0, s57, 0xffffff80
	s_nop 0
	global_load_lds_dwordx4 v132, s[34:35] offset:128
	s_waitcnt vmcnt(8)
	s_waitcnt lgkmcnt(0)
	s_barrier
	v_mfma_f32_16x16x32_bf16 v[62:65], v[158:161], v[190:193], v[62:65]
	v_mfma_f32_16x16x32_bf16 v[58:61], v[166:169], v[190:193], v[58:61]
	v_mfma_f32_16x16x32_bf16 v[50:53], v[158:161], v[206:209], v[50:53]
	v_mfma_f32_16x16x32_bf16 v[42:45], v[166:169], v[206:209], v[42:45]
	v_mfma_f32_16x16x32_bf16 v[34:37], v[158:161], v[214:217], v[34:37]
	v_mfma_f32_16x16x32_bf16 v[26:29], v[166:169], v[214:217], v[26:29]
	v_mfma_f32_16x16x32_bf16 v[18:21], v[158:161], v[222:225], v[18:21]
	v_mfma_f32_16x16x32_bf16 v[10:13], v[166:169], v[222:225], v[10:13]
	v_mfma_f32_16x16x32_bf16 v[62:65], v[162:165], v[194:197], v[62:65]
	v_mfma_f32_16x16x32_bf16 v[58:61], v[170:173], v[194:197], v[58:61]
	v_mfma_f32_16x16x32_bf16 v[50:53], v[162:165], v[210:213], v[50:53]
	v_mfma_f32_16x16x32_bf16 v[42:45], v[170:173], v[210:213], v[42:45]
	v_mfma_f32_16x16x32_bf16 v[34:37], v[162:165], v[218:221], v[34:37]
	v_mfma_f32_16x16x32_bf16 v[26:29], v[170:173], v[218:221], v[26:29]
	v_mfma_f32_16x16x32_bf16 v[18:21], v[162:165], v[226:229], v[18:21]
	v_mfma_f32_16x16x32_bf16 v[10:13], v[170:173], v[226:229], v[10:13]
	v_mfma_f32_16x16x32_bf16 v[54:57], v[174:177], v[190:193], v[54:57]
	v_mfma_f32_16x16x32_bf16 v[46:49], v[182:185], v[190:193], v[46:49]
	v_mfma_f32_16x16x32_bf16 v[38:41], v[174:177], v[206:209], v[38:41]
	v_mfma_f32_16x16x32_bf16 v[30:33], v[182:185], v[206:209], v[30:33]
	v_mfma_f32_16x16x32_bf16 v[22:25], v[174:177], v[214:217], v[22:25]
	v_mfma_f32_16x16x32_bf16 v[14:17], v[182:185], v[214:217], v[14:17]
	v_mfma_f32_16x16x32_bf16 v[6:9], v[174:177], v[222:225], v[6:9]
	v_mfma_f32_16x16x32_bf16 v[2:5], v[182:185], v[222:225], v[2:5]
	v_mfma_f32_16x16x32_bf16 v[54:57], v[178:181], v[194:197], v[54:57]
	v_mfma_f32_16x16x32_bf16 v[46:49], v[186:189], v[194:197], v[46:49]
	v_mfma_f32_16x16x32_bf16 v[38:41], v[178:181], v[210:213], v[38:41]
	v_mfma_f32_16x16x32_bf16 v[30:33], v[186:189], v[210:213], v[30:33]
	v_mfma_f32_16x16x32_bf16 v[22:25], v[178:181], v[218:221], v[22:25]
	v_mfma_f32_16x16x32_bf16 v[14:17], v[186:189], v[218:221], v[14:17]
	v_mfma_f32_16x16x32_bf16 v[6:9], v[178:181], v[226:229], v[6:9]
	v_mfma_f32_16x16x32_bf16 v[2:5], v[186:189], v[226:229], v[2:5]
	s_barrier
	s_add_i32 s40, s40, 2
	s_add_u32 s8, s8, 0x100
	s_addc_u32 s9, s9, 0
	s_add_u32 s38, s38, 0x100
	s_addc_u32 s39, s39, 0
	s_cmp_gt_u32 s40, 13
	s_cbranch_scc0 .LBB0_114
	s_and_b64 vcc, exec, s[6:7]
	s_cbranch_vccz .LBB0_117
	s_barrier

; #define PG8_STAGE(bufoff, gbase, voff) do { _Pragma("unroll") for (int _i = 0; _i < 2; ++_i) \
;         __builtin_amdgcn_global_load_lds((const unsigned*)((const char*)(gbase) + (voff)[_i]), (PG8_LAS unsigned*)(lds + (bufoff) + ldsw + _i * 8192), 16, 0, 0); } while (0)
; #define PG8_LDA(dst, b, h) do { _Pragma("unroll") for (int m = 0; m < 4; ++m) _Pragma("unroll") for (int k = 0; k < 2; ++k) dst[m][k] = *(const PG8_LAS bf16x8*)(lds + PG8_SA(b, h) + aoff + m * 2048 + k * 1024); } while (0)
; #define PG8_LDB(dst, b, h) do { _Pragma("unroll") for (int n = 0; n < 2; ++n) _Pragma("unroll") for (int k = 0; k < 2; ++k) dst[n][k] = *(const PG8_LAS bf16x8*)(lds + PG8_SB(b, h) + boff + n * 2048 + k * 1024); } while (0)
; #define PG8_MMA(ai, bj, At, Bt) do { __builtin_amdgcn_s_setprio(1); _Pragma("unroll") for (int m = 0; m < 4; ++m) _Pragma("unroll") for (int n = 0; n < 2; ++n) _Pragma("unroll") for (int k = 0; k < 2; ++k) \
;         acc[ai][bj][m][n] = __builtin_amdgcn_mfma_f32_16x16x32_bf16(Bt[n][k], At[m][k], acc[ai][bj][m][n], 0, 0, 0); __builtin_amdgcn_s_setprio(0); } while (0)
; #define PG8_WAIT_V(n) asm volatile("s_waitcnt vmcnt(" #n ")" ::: "memory")
; #define PG8_WAIT_L(n) asm volatile("s_waitcnt lgkmcnt(" #n ")" ::: "memory")
; template <class Epi, class Sched, bool ALIGN_EPI = false, bool SP2 = false>
; __device__ __forceinline__ void gemm_phase(PG8_LAS unsigned char* lds, const Gemm g, const Sched& S, const Epi& E) {
;     ...
;             const bool last = (t == nt - 2);
;             const char* a1 = cA + (size_t)(t + 1) * kstep;
;             const char* a2 = last ? nA : cA + (size_t)(t + 2) * kstep; const char* b2 = last ? nB : cB + (size_t)(t + 2) * kstep;
;             const char* a3 = a2 + kstep; const char* b3 = b2 + kstep;
;             if (last && has_next) S.a_ready(nxt);
;             if constexpr (SP2) {
;             PG8_LDB(B0, 0, 0); PG8_LDB(B1, 0, 1); PG8_SCHED; PG8_LDA(At, 0, 0); PG8_STAGE(PG8_SA(1, 1), a1 + hstep, voffA);
;             PG8_WAIT_V(8); PG8_WAIT_L(0); PG8_BAR; PG8_MMA(0, 0, At, B0); PG8_MMA(0, 1, At, B1); PG8_BAR; PG8_SCHED;
;             PG8_LDA(At, 0, 1); PG8_STAGE(PG8_SB(0, 0), b2, voffB); PG8_STAGE(PG8_SB(0, 1), b2 + hstep, voffB); PG8_STAGE(PG8_SA(0, 0), a2, voffA);
;             PG8_WAIT_V(8); PG8_WAIT_L(0); PG8_BAR; PG8_MMA(1, 0, At, B0); PG8_MMA(1, 1, At, B1); PG8_BAR; PG8_SCHED;
.LBB0_144:
	s_add_u32 s20, s8, 0xfffc0080
	s_addc_u32 s21, s9, -1
	s_add_i32 s80, 0, 0x10000
	s_cmp_eq_u32 s73, 12
	s_cselect_b32 s39, s17, s21
	s_cselect_b32 s38, s40, s20
	v_add_u32_e32 v149, s80, v147
	s_cselect_b32 s35, s13, s72
	s_cselect_b32 s34, s41, s46
	s_add_i32 s20, 0, 0x14000
	ds_read_b128 v[142:145], v149
	ds_read_b128 v[150:153], v149 offset:1024
	ds_read_b128 v[154:157], v149 offset:2048
	ds_read_b128 v[158:161], v149 offset:3072
	v_add_u32_e32 v149, s20, v147
	ds_read_b128 v[162:165], v149
	ds_read_b128 v[166:169], v149 offset:1024
	ds_read_b128 v[170:173], v149 offset:2048
	ds_read_b128 v[174:177], v149 offset:3072
	s_add_i32 m0, s28, 0xc000
	ds_read_b128 v[178:181], v148
	ds_read_b128 v[182:185], v148 offset:1024
	ds_read_b128 v[186:189], v148 offset:2048
	ds_read_b128 v[190:193], v148 offset:3072
	ds_read_b128 v[194:197], v148 offset:4096
	ds_read_b128 v[206:209], v148 offset:5120
	ds_read_b128 v[210:213], v148 offset:6144
	ds_read_b128 v[214:217], v148 offset:7168
	global_load_lds_dwordx4 v138, s[8:9]
	s_add_i32 m0, s28, 0xe000
	s_nop 0
	global_load_lds_dwordx4 v140, s[8:9]
	s_waitcnt vmcnt(8)
	s_waitcnt lgkmcnt(0)
	s_barrier
	v_mfma_f32_16x16x32_bf16 v[126:129], v[142:145], v[178:181], v[126:129]
	v_mfma_f32_16x16x32_bf16 v[122:125], v[154:157], v[178:181], v[122:125]
	v_mfma_f32_16x16x32_bf16 v[110:113], v[142:145], v[186:189], v[110:113]
	v_mfma_f32_16x16x32_bf16 v[106:109], v[154:157], v[186:189], v[106:109]
	v_mfma_f32_16x16x32_bf16 v[94:97], v[142:145], v[194:197], v[94:97]
	v_mfma_f32_16x16x32_bf16 v[90:93], v[154:157], v[194:197], v[90:93]
	v_mfma_f32_16x16x32_bf16 v[78:81], v[142:145], v[210:213], v[78:81]
	v_mfma_f32_16x16x32_bf16 v[74:77], v[154:157], v[210:213], v[74:77]
	v_mfma_f32_16x16x32_bf16 v[126:129], v[150:153], v[182:185], v[126:129]
	v_mfma_f32_16x16x32_bf16 v[122:125], v[158:161], v[182:185], v[122:125]
	v_mfma_f32_16x16x32_bf16 v[110:113], v[150:153], v[190:193], v[110:113]
	v_mfma_f32_16x16x32_bf16 v[106:109], v[158:161], v[190:193], v[106:109]
	v_mfma_f32_16x16x32_bf16 v[94:97], v[150:153], v[206:209], v[94:97]
	v_mfma_f32_16x16x32_bf16 v[90:93], v[158:161], v[206:209], v[90:93]
	v_mfma_f32_16x16x32_bf16 v[78:81], v[150:153], v[214:217], v[78:81]
	v_mfma_f32_16x16x32_bf16 v[74:77], v[158:161], v[214:217], v[74:77]
	v_mfma_f32_16x16x32_bf16 v[118:121], v[162:165], v[178:181], v[118:121]
	v_mfma_f32_16x16x32_bf16 v[114:117], v[170:173], v[178:181], v[114:117]
	v_mfma_f32_16x16x32_bf16 v[102:105], v[162:165], v[186:189], v[102:105]
	v_mfma_f32_16x16x32_bf16 v[98:101], v[170:173], v[186:189], v[98:101]
	v_mfma_f32_16x16x32_bf16 v[86:89], v[162:165], v[194:197], v[86:89]
	v_mfma_f32_16x16x32_bf16 v[82:85], v[170:173], v[194:197], v[82:85]
	v_mfma_f32_16x16x32_bf16 v[70:73], v[162:165], v[210:213], v[70:73]
	v_mfma_f32_16x16x32_bf16 v[66:69], v[170:173], v[210:213], v[66:69]
	v_mfma_f32_16x16x32_bf16 v[118:121], v[166:169], v[182:185], v[118:121]
	v_mfma_f32_16x16x32_bf16 v[114:117], v[174:177], v[182:185], v[114:117]
	v_mfma_f32_16x16x32_bf16 v[102:105], v[166:169], v[190:193], v[102:105]
	v_mfma_f32_16x16x32_bf16 v[98:101], v[174:177], v[190:193], v[98:101]
	v_mfma_f32_16x16x32_bf16 v[86:89], v[166:169], v[206:209], v[86:89]
	v_mfma_f32_16x16x32_bf16 v[82:85], v[174:177], v[206:209], v[82:85]
	v_mfma_f32_16x16x32_bf16 v[70:73], v[166:169], v[214:217], v[70:73]
	v_mfma_f32_16x16x32_bf16 v[66:69], v[174:177], v[214:217], v[66:69]
	s_barrier
	s_add_i32 s21, s80, s47
	s_mov_b32 m0, s21
	ds_read_b128 v[178:181], v148 offset:16384
	ds_read_b128 v[182:185], v148 offset:17408
	ds_read_b128 v[186:189], v148 offset:18432
	ds_read_b128 v[190:193], v148 offset:19456
	ds_read_b128 v[194:197], v148 offset:20480
	ds_read_b128 v[206:209], v148 offset:21504
	ds_read_b128 v[210:213], v148 offset:22528
	ds_read_b128 v[214:217], v148 offset:23552
	global_load_lds_dwordx4 v0, s[34:35]
	s_add_i32 m0, s21, 0x2000
	s_add_u32 s82, s34, 0x40000
	s_addc_u32 s83, s35, 0
	s_add_i32 s20, s20, s47
	global_load_lds_dwordx4 v130, s[34:35]
	s_mov_b32 m0, s20
	s_nop 0
	global_load_lds_dwordx4 v0, s[82:83]
	s_add_i32 m0, s20, 0x2000
	s_nop 0
	global_load_lds_dwordx4 v130, s[82:83]
	s_mov_b32 m0, s28
	s_nop 0
	global_load_lds_dwordx4 v134, s[38:39]
	s_mov_b32 m0, s29
	s_nop 0
	global_load_lds_dwordx4 v132, s[38:39]
	s_waitcnt vmcnt(8)
	s_waitcnt lgkmcnt(0)
	s_barrier
	v_mfma_f32_16x16x32_bf16 v[62:65], v[142:145], v[178:181], v[62:65]
	v_mfma_f32_16x16x32_bf16 v[58:61], v[154:157], v[178:181], v[58:61]
	v_mfma_f32_16x16x32_bf16 v[46:49], v[142:145], v[186:189], v[46:49]
	v_mfma_f32_16x16x32_bf16 v[42:45], v[154:157], v[186:189], v[42:45]
	v_mfma_f32_16x16x32_bf16 v[30:33], v[142:145], v[194:197], v[30:33]
	v_mfma_f32_16x16x32_bf16 v[26:29], v[154:157], v[194:197], v[26:29]
	v_mfma_f32_16x16x32_bf16 v[14:17], v[142:145], v[210:213], v[14:17]
	v_mfma_f32_16x16x32_bf16 v[10:13], v[154:157], v[210:213], v[10:13]
	v_mfma_f32_16x16x32_bf16 v[62:65], v[150:153], v[182:185], v[62:65]
	v_mfma_f32_16x16x32_bf16 v[58:61], v[158:161], v[182:185], v[58:61]
	v_mfma_f32_16x16x32_bf16 v[46:49], v[150:153], v[190:193], v[46:49]
	v_mfma_f32_16x16x32_bf16 v[42:45], v[158:161], v[190:193], v[42:45]
	v_mfma_f32_16x16x32_bf16 v[30:33], v[150:153], v[206:209], v[30:33]
	v_mfma_f32_16x16x32_bf16 v[26:29], v[158:161], v[206:209], v[26:29]
	v_mfma_f32_16x16x32_bf16 v[14:17], v[150:153], v[214:217], v[14:17]
	v_mfma_f32_16x16x32_bf16 v[10:13], v[158:161], v[214:217], v[10:13]
	v_mfma_f32_16x16x32_bf16 v[54:57], v[162:165], v[178:181], v[54:57]
	v_mfma_f32_16x16x32_bf16 v[50:53], v[170:173], v[178:181], v[50:53]
	v_mfma_f32_16x16x32_bf16 v[38:41], v[162:165], v[186:189], v[38:41]
	v_mfma_f32_16x16x32_bf16 v[34:37], v[170:173], v[186:189], v[34:37]
	v_mfma_f32_16x16x32_bf16 v[22:25], v[162:165], v[194:197], v[22:25]
	v_mfma_f32_16x16x32_bf16 v[18:21], v[170:173], v[194:197], v[18:21]
	v_mfma_f32_16x16x32_bf16 v[6:9], v[162:165], v[210:213], v[6:9]
	v_mfma_f32_16x16x32_bf16 v[2:5], v[170:173], v[210:213], v[2:5]
	v_mfma_f32_16x16x32_bf16 v[54:57], v[166:169], v[182:185], v[54:57]
	v_mfma_f32_16x16x32_bf16 v[50:53], v[174:177], v[182:185], v[50:53]
	v_mfma_f32_16x16x32_bf16 v[38:41], v[166:169], v[190:193], v[38:41]
	v_mfma_f32_16x16x32_bf16 v[34:37], v[174:177], v[190:193], v[34:37]
	v_mfma_f32_16x16x32_bf16 v[22:25], v[166:169], v[206:209], v[22:25]
	v_mfma_f32_16x16x32_bf16 v[18:21], v[174:177], v[206:209], v[18:21]
	v_mfma_f32_16x16x32_bf16 v[6:9], v[166:169], v[214:217], v[6:9]
	v_mfma_f32_16x16x32_bf16 v[2:5], v[174:177], v[214:217], v[2:5]
	s_barrier
; #define PG8_STAGE(bufoff, gbase, voff) do { _Pragma("unroll") for (int _i = 0; _i < 2; ++_i) \
;         __builtin_amdgcn_global_load_lds((const unsigned*)((const char*)(gbase) + (voff)[_i]), (PG8_LAS unsigned*)(lds + (bufoff) + ldsw + _i * 8192), 16, 0, 0); } while (0)
; #define PG8_LDA(dst, b, h) do { _Pragma("unroll") for (int m = 0; m < 4; ++m) _Pragma("unroll") for (int k = 0; k < 2; ++k) dst[m][k] = *(const PG8_LAS bf16x8*)(lds + PG8_SA(b, h) + aoff + m * 2048 + k * 1024); } while (0)
; #define PG8_LDB(dst, b, h) do { _Pragma("unroll") for (int n = 0; n < 2; ++n) _Pragma("unroll") for (int k = 0; k < 2; ++k) dst[n][k] = *(const PG8_LAS bf16x8*)(lds + PG8_SB(b, h) + boff + n * 2048 + k * 1024); } while (0)
; #define PG8_MMA(ai, bj, At, Bt) do { __builtin_amdgcn_s_setprio(1); _Pragma("unroll") for (int m = 0; m < 4; ++m) _Pragma("unroll") for (int n = 0; n < 2; ++n) _Pragma("unroll") for (int k = 0; k < 2; ++k) \
;         acc[ai][bj][m][n] = __builtin_amdgcn_mfma_f32_16x16x32_bf16(Bt[n][k], At[m][k], acc[ai][bj][m][n], 0, 0, 0); __builtin_amdgcn_s_setprio(0); } while (0)
; #define PG8_WAIT_V(n) asm volatile("s_waitcnt vmcnt(" #n ")" ::: "memory")
; #define PG8_WAIT_L(n) asm volatile("s_waitcnt lgkmcnt(" #n ")" ::: "memory")
; #define PG8_BAR __builtin_amdgcn_s_barrier()
; #define PG8_SCHED __builtin_amdgcn_sched_barrier(0)
; template <class Epi, class Sched, bool ALIGN_EPI = false, bool SP2 = false>
; __device__ __forceinline__ void gemm_phase(PG8_LAS unsigned char* lds, const Gemm g, const Sched& S, const Epi& E) {
;     ...
;             PG8_LDB(B0, 1, 0); PG8_LDB(B1, 1, 1); PG8_SCHED; PG8_LDA(At, 1, 0); PG8_STAGE(PG8_SA(0, 1), a2 + hstep, voffA);
;             PG8_WAIT_V(8); PG8_WAIT_L(0); PG8_BAR; PG8_MMA(0, 0, At, B0); PG8_MMA(0, 1, At, B1); PG8_BAR; PG8_SCHED;
;             PG8_LDA(At, 1, 1); PG8_STAGE(PG8_SB(1, 0), b3, voffB); PG8_STAGE(PG8_SB(1, 1), b3 + hstep, voffB); PG8_STAGE(PG8_SA(1, 0), a3, voffA);
;             PG8_WAIT_V(8); PG8_WAIT_L(0); PG8_BAR; PG8_MMA(1, 0, At, B0); PG8_MMA(1, 1, At, B1); PG8_BAR; PG8_SCHED;
	s_add_i32 s20, 0, 0x18000
	v_add_u32_e32 v149, s20, v147
	s_add_i32 s21, 0, 0x1c000
	ds_read_b128 v[142:145], v149
	ds_read_b128 v[150:153], v149 offset:1024
	ds_read_b128 v[154:157], v149 offset:2048
	ds_read_b128 v[158:161], v149 offset:3072
	v_add_u32_e32 v149, s21, v147
	ds_read_b128 v[162:165], v149
	ds_read_b128 v[166:169], v149 offset:1024
	ds_read_b128 v[170:173], v149 offset:2048
	ds_read_b128 v[174:177], v149 offset:3072
	s_add_u32 vcc_lo, s38, 0x40000
	s_addc_u32 vcc_hi, s39, 0
	s_mov_b32 m0, s52
	ds_read_b128 v[178:181], v148 offset:32768
	ds_read_b128 v[182:185], v148 offset:33792
	ds_read_b128 v[186:189], v148 offset:34816
	ds_read_b128 v[190:193], v148 offset:35840
	ds_read_b128 v[194:197], v148 offset:36864
	ds_read_b128 v[206:209], v148 offset:37888
	ds_read_b128 v[210:213], v148 offset:38912
	ds_read_b128 v[214:217], v148 offset:39936
	global_load_lds_dwordx4 v134, vcc
	s_mov_b32 m0, s53
	s_nop 0
	global_load_lds_dwordx4 v132, vcc
	s_waitcnt vmcnt(8)
	s_waitcnt lgkmcnt(0)
	s_barrier
	v_mfma_f32_16x16x32_bf16 v[126:129], v[142:145], v[178:181], v[126:129]
	v_mfma_f32_16x16x32_bf16 v[122:125], v[154:157], v[178:181], v[122:125]
	v_mfma_f32_16x16x32_bf16 v[110:113], v[142:145], v[186:189], v[110:113]
	v_mfma_f32_16x16x32_bf16 v[106:109], v[154:157], v[186:189], v[106:109]
	v_mfma_f32_16x16x32_bf16 v[94:97], v[142:145], v[194:197], v[94:97]
	v_mfma_f32_16x16x32_bf16 v[90:93], v[154:157], v[194:197], v[90:93]
	v_mfma_f32_16x16x32_bf16 v[78:81], v[142:145], v[210:213], v[78:81]
	v_mfma_f32_16x16x32_bf16 v[74:77], v[154:157], v[210:213], v[74:77]
	v_mfma_f32_16x16x32_bf16 v[126:129], v[150:153], v[182:185], v[126:129]
	v_mfma_f32_16x16x32_bf16 v[122:125], v[158:161], v[182:185], v[122:125]
	v_mfma_f32_16x16x32_bf16 v[110:113], v[150:153], v[190:193], v[110:113]
	v_mfma_f32_16x16x32_bf16 v[106:109], v[158:161], v[190:193], v[106:109]
	v_mfma_f32_16x16x32_bf16 v[94:97], v[150:153], v[206:209], v[94:97]
	v_mfma_f32_16x16x32_bf16 v[90:93], v[158:161], v[206:209], v[90:93]
	v_mfma_f32_16x16x32_bf16 v[78:81], v[150:153], v[214:217], v[78:81]
	v_mfma_f32_16x16x32_bf16 v[74:77], v[158:161], v[214:217], v[74:77]
	v_mfma_f32_16x16x32_bf16 v[118:121], v[162:165], v[178:181], v[118:121]
	v_mfma_f32_16x16x32_bf16 v[114:117], v[170:173], v[178:181], v[114:117]
	v_mfma_f32_16x16x32_bf16 v[102:105], v[162:165], v[186:189], v[102:105]
	v_mfma_f32_16x16x32_bf16 v[98:101], v[170:173], v[186:189], v[98:101]
	v_mfma_f32_16x16x32_bf16 v[86:89], v[162:165], v[194:197], v[86:89]
	v_mfma_f32_16x16x32_bf16 v[82:85], v[170:173], v[194:197], v[82:85]
	v_mfma_f32_16x16x32_bf16 v[70:73], v[162:165], v[210:213], v[70:73]
	v_mfma_f32_16x16x32_bf16 v[66:69], v[170:173], v[210:213], v[66:69]
	v_mfma_f32_16x16x32_bf16 v[118:121], v[166:169], v[182:185], v[118:121]
	v_mfma_f32_16x16x32_bf16 v[114:117], v[174:177], v[182:185], v[114:117]
	v_mfma_f32_16x16x32_bf16 v[102:105], v[166:169], v[190:193], v[102:105]
	v_mfma_f32_16x16x32_bf16 v[98:101], v[174:177], v[190:193], v[98:101]
	v_mfma_f32_16x16x32_bf16 v[86:89], v[166:169], v[206:209], v[86:89]
	v_mfma_f32_16x16x32_bf16 v[82:85], v[174:177], v[206:209], v[82:85]
	v_mfma_f32_16x16x32_bf16 v[70:73], v[166:169], v[214:217], v[70:73]
	v_mfma_f32_16x16x32_bf16 v[66:69], v[174:177], v[214:217], v[66:69]
	s_barrier
	s_add_i32 s20, s20, s47
	s_add_i32 m0, s20, 0xffffff80
	ds_read_b128 v[178:181], v148 offset:49152
	ds_read_b128 v[182:185], v148 offset:50176
	ds_read_b128 v[186:189], v148 offset:51200
	ds_read_b128 v[190:193], v148 offset:52224
	ds_read_b128 v[194:197], v148 offset:53248
	ds_read_b128 v[206:209], v148 offset:54272
	ds_read_b128 v[210:213], v148 offset:55296
	ds_read_b128 v[214:217], v148 offset:56320
	global_load_lds_dwordx4 v0, s[34:35] offset:128
	s_add_i32 m0, s20, 0x1f80
	s_add_i32 s20, s21, s47
	global_load_lds_dwordx4 v130, s[34:35] offset:128
	s_add_u32 s34, s34, 0x40080
	s_addc_u32 s35, s35, 0
	s_mov_b32 m0, s20
	s_nop 0
	global_load_lds_dwordx4 v0, s[34:35]
	s_add_i32 m0, s20, 0x2000
	s_nop 0
	global_load_lds_dwordx4 v130, s[34:35]
	s_add_i32 m0, s55, 0xffffff80
	s_nop 0
	global_load_lds_dwordx4 v134, s[38:39] offset:128
	s_add_i32 m0, s57, 0xffffff80
	s_nop 0
	global_load_lds_dwordx4 v132, s[38:39] offset:128
	s_waitcnt vmcnt(8)
	s_waitcnt lgkmcnt(0)
	s_barrier
	v_mfma_f32_16x16x32_bf16 v[62:65], v[142:145], v[178:181], v[62:65]
	v_mfma_f32_16x16x32_bf16 v[58:61], v[154:157], v[178:181], v[58:61]
	v_mfma_f32_16x16x32_bf16 v[46:49], v[142:145], v[186:189], v[46:49]
	v_mfma_f32_16x16x32_bf16 v[42:45], v[154:157], v[186:189], v[42:45]
	v_mfma_f32_16x16x32_bf16 v[30:33], v[142:145], v[194:197], v[30:33]
	v_mfma_f32_16x16x32_bf16 v[26:29], v[154:157], v[194:197], v[26:29]
	v_mfma_f32_16x16x32_bf16 v[14:17], v[142:145], v[210:213], v[14:17]
	v_mfma_f32_16x16x32_bf16 v[10:13], v[154:157], v[210:213], v[10:13]
	v_mfma_f32_16x16x32_bf16 v[62:65], v[150:153], v[182:185], v[62:65]
	v_mfma_f32_16x16x32_bf16 v[58:61], v[158:161], v[182:185], v[58:61]
	v_mfma_f32_16x16x32_bf16 v[46:49], v[150:153], v[190:193], v[46:49]
	v_mfma_f32_16x16x32_bf16 v[42:45], v[158:161], v[190:193], v[42:45]
	v_mfma_f32_16x16x32_bf16 v[30:33], v[150:153], v[206:209], v[30:33]
	v_mfma_f32_16x16x32_bf16 v[26:29], v[158:161], v[206:209], v[26:29]
	v_mfma_f32_16x16x32_bf16 v[14:17], v[150:153], v[214:217], v[14:17]
	v_mfma_f32_16x16x32_bf16 v[10:13], v[158:161], v[214:217], v[10:13]
	v_mfma_f32_16x16x32_bf16 v[54:57], v[162:165], v[178:181], v[54:57]
	v_mfma_f32_16x16x32_bf16 v[50:53], v[170:173], v[178:181], v[50:53]
	v_mfma_f32_16x16x32_bf16 v[38:41], v[162:165], v[186:189], v[38:41]
	v_mfma_f32_16x16x32_bf16 v[34:37], v[170:173], v[186:189], v[34:37]
	v_mfma_f32_16x16x32_bf16 v[22:25], v[162:165], v[194:197], v[22:25]
	v_mfma_f32_16x16x32_bf16 v[18:21], v[170:173], v[194:197], v[18:21]
	v_mfma_f32_16x16x32_bf16 v[6:9], v[162:165], v[210:213], v[6:9]
	v_mfma_f32_16x16x32_bf16 v[2:5], v[170:173], v[210:213], v[2:5]
	v_mfma_f32_16x16x32_bf16 v[54:57], v[166:169], v[182:185], v[54:57]
	v_mfma_f32_16x16x32_bf16 v[50:53], v[174:177], v[182:185], v[50:53]
	v_mfma_f32_16x16x32_bf16 v[38:41], v[166:169], v[190:193], v[38:41]
	v_mfma_f32_16x16x32_bf16 v[34:37], v[174:177], v[190:193], v[34:37]
	v_mfma_f32_16x16x32_bf16 v[22:25], v[166:169], v[206:209], v[22:25]
	v_mfma_f32_16x16x32_bf16 v[18:21], v[174:177], v[206:209], v[18:21]
	v_mfma_f32_16x16x32_bf16 v[6:9], v[166:169], v[214:217], v[6:9]
	v_mfma_f32_16x16x32_bf16 v[2:5], v[174:177], v[214:217], v[2:5]
	s_barrier
	s_add_i32 s73, s73, 2
	s_add_u32 s8, s8, 0x100
	s_addc_u32 s9, s9, 0
	s_add_u32 s46, s46, 0x100
	s_addc_u32 s72, s72, 0
	s_cmp_gt_u32 s73, 13
	s_cbranch_scc0 .LBB0_144
	s_and_b64 vcc, exec, s[6:7]
	s_cbranch_vccz .LBB0_147
	s_barrier

; #define PG8_STAGE(bufoff, gbase, voff) do { _Pragma("unroll") for (int _i = 0; _i < 2; ++_i) \
;         __builtin_amdgcn_global_load_lds((const unsigned*)((const char*)(gbase) + (voff)[_i]), (PG8_LAS unsigned*)(lds + (bufoff) + ldsw + _i * 8192), 16, 0, 0); } while (0)
; #define PG8_LDA(dst, b, h) do { _Pragma("unroll") for (int m = 0; m < 4; ++m) _Pragma("unroll") for (int k = 0; k < 2; ++k) dst[m][k] = *(const PG8_LAS bf16x8*)(lds + PG8_SA(b, h) + aoff + m * 2048 + k * 1024); } while (0)
; #define PG8_LDB(dst, b, h) do { _Pragma("unroll") for (int n = 0; n < 2; ++n) _Pragma("unroll") for (int k = 0; k < 2; ++k) dst[n][k] = *(const PG8_LAS bf16x8*)(lds + PG8_SB(b, h) + boff + n * 2048 + k * 1024); } while (0)
; #define PG8_MMA(ai, bj, At, Bt) do { __builtin_amdgcn_s_setprio(1); _Pragma("unroll") for (int m = 0; m < 4; ++m) _Pragma("unroll") for (int n = 0; n < 2; ++n) _Pragma("unroll") for (int k = 0; k < 2; ++k) \
;         acc[ai][bj][m][n] = __builtin_amdgcn_mfma_f32_16x16x32_bf16(Bt[n][k], At[m][k], acc[ai][bj][m][n], 0, 0, 0); __builtin_amdgcn_s_setprio(0); } while (0)
; #define PG8_WAIT_V(n) asm volatile("s_waitcnt vmcnt(" #n ")" ::: "memory")
; #define PG8_WAIT_L(n) asm volatile("s_waitcnt lgkmcnt(" #n ")" ::: "memory")
; template <class Epi, class Sched, bool ALIGN_EPI = false, bool SP2 = false>
; __device__ __forceinline__ void gemm_phase(PG8_LAS unsigned char* lds, const Gemm g, const Sched& S, const Epi& E) {
;     ...
;             const bool last = (t == nt - 2);
;             const char* a1 = cA + (size_t)(t + 1) * kstep;
;             const char* a2 = last ? nA : cA + (size_t)(t + 2) * kstep; const char* b2 = last ? nB : cB + (size_t)(t + 2) * kstep;
;             const char* a3 = a2 + kstep; const char* b3 = b2 + kstep;
;             if (last && has_next) S.a_ready(nxt);
;             if constexpr (SP2) {
;             PG8_LDB(B0, 0, 0); PG8_LDB(B1, 0, 1); PG8_SCHED; PG8_LDA(At, 0, 0); PG8_STAGE(PG8_SA(1, 1), a1 + hstep, voffA);
;             PG8_WAIT_V(8); PG8_WAIT_L(0); PG8_BAR; PG8_MMA(0, 0, At, B0); PG8_MMA(0, 1, At, B1); PG8_BAR; PG8_SCHED;
;             PG8_LDA(At, 0, 1); PG8_STAGE(PG8_SB(0, 0), b2, voffB); PG8_STAGE(PG8_SB(0, 1), b2 + hstep, voffB); PG8_STAGE(PG8_SA(0, 0), a2, voffA);
;             PG8_WAIT_V(8); PG8_WAIT_L(0); PG8_BAR; PG8_MMA(1, 0, At, B0); PG8_MMA(1, 1, At, B1); PG8_BAR; PG8_SCHED;
.LBB0_351:
	s_add_u32 s20, s8, 0xfffc0080
	s_addc_u32 s21, s9, -1
	s_add_i32 s80, 0, 0x10000
	s_cmp_eq_u32 s73, 12
	s_cselect_b32 s35, s17, s21
	s_cselect_b32 s34, s40, s20
	s_cselect_b32 s31, s13, s72
	s_cselect_b32 s30, s41, s58
	s_add_i32 s81, 0, 0x14000
	v_add_u32_e32 v148, s80, v153
	v_add_u32_e32 v168, s81, v153
	ds_read_b128 v[130:133], v148
	ds_read_b128 v[134:137], v148 offset:1024
	ds_read_b128 v[138:141], v148 offset:2048
	ds_read_b128 v[148:151], v148 offset:3072
	ds_read_b128 v[156:159], v168
	ds_read_b128 v[160:163], v168 offset:1024
	ds_read_b128 v[164:167], v168 offset:2048
	ds_read_b128 v[168:171], v168 offset:3072
	v_lshl_add_u64 v[196:197], s[8:9], 0, v[144:145]
	s_add_i32 m0, s43, 0xc000
	ds_read_b128 v[172:175], v155
	ds_read_b128 v[176:179], v155 offset:1024
	ds_read_b128 v[180:183], v155 offset:2048
	ds_read_b128 v[184:187], v155 offset:3072
	ds_read_b128 v[188:191], v155 offset:4096
	ds_read_b128 v[192:195], v155 offset:5120
	ds_read_b128 v[206:209], v155 offset:6144
	ds_read_b128 v[210:213], v155 offset:7168
	global_load_lds_dwordx4 v[196:197], off
	s_add_i32 m0, s43, 0xe000
	v_lshl_add_u64 v[196:197], s[8:9], 0, v[146:147]
	global_load_lds_dwordx4 v[196:197], off
	s_waitcnt vmcnt(8)
	s_waitcnt lgkmcnt(0)
	s_barrier
	v_mfma_f32_16x16x32_bf16 v[126:129], v[130:133], v[172:175], v[126:129]
	v_mfma_f32_16x16x32_bf16 v[122:125], v[138:141], v[172:175], v[122:125]
	v_mfma_f32_16x16x32_bf16 v[118:121], v[130:133], v[180:183], v[118:121]
	v_mfma_f32_16x16x32_bf16 v[106:109], v[138:141], v[180:183], v[106:109]
	v_mfma_f32_16x16x32_bf16 v[102:105], v[130:133], v[188:191], v[102:105]
	v_mfma_f32_16x16x32_bf16 v[90:93], v[138:141], v[188:191], v[90:93]
	v_mfma_f32_16x16x32_bf16 v[86:89], v[130:133], v[206:209], v[86:89]
	v_mfma_f32_16x16x32_bf16 v[74:77], v[138:141], v[206:209], v[74:77]
	v_mfma_f32_16x16x32_bf16 v[126:129], v[134:137], v[176:179], v[126:129]
	v_mfma_f32_16x16x32_bf16 v[122:125], v[148:151], v[176:179], v[122:125]
	v_mfma_f32_16x16x32_bf16 v[118:121], v[134:137], v[184:187], v[118:121]
	v_mfma_f32_16x16x32_bf16 v[106:109], v[148:151], v[184:187], v[106:109]
	v_mfma_f32_16x16x32_bf16 v[102:105], v[134:137], v[192:195], v[102:105]
	v_mfma_f32_16x16x32_bf16 v[90:93], v[148:151], v[192:195], v[90:93]
	v_mfma_f32_16x16x32_bf16 v[86:89], v[134:137], v[210:213], v[86:89]
	v_mfma_f32_16x16x32_bf16 v[74:77], v[148:151], v[210:213], v[74:77]
	v_mfma_f32_16x16x32_bf16 v[114:117], v[156:159], v[172:175], v[114:117]
	v_mfma_f32_16x16x32_bf16 v[110:113], v[164:167], v[172:175], v[110:113]
	v_mfma_f32_16x16x32_bf16 v[98:101], v[156:159], v[180:183], v[98:101]
	v_mfma_f32_16x16x32_bf16 v[94:97], v[164:167], v[180:183], v[94:97]
	v_mfma_f32_16x16x32_bf16 v[82:85], v[156:159], v[188:191], v[82:85]
	v_mfma_f32_16x16x32_bf16 v[78:81], v[164:167], v[188:191], v[78:81]
	v_mfma_f32_16x16x32_bf16 v[70:73], v[156:159], v[206:209], v[70:73]
	v_mfma_f32_16x16x32_bf16 v[66:69], v[164:167], v[206:209], v[66:69]
	v_mfma_f32_16x16x32_bf16 v[114:117], v[160:163], v[176:179], v[114:117]
	v_mfma_f32_16x16x32_bf16 v[110:113], v[168:171], v[176:179], v[110:113]
	v_mfma_f32_16x16x32_bf16 v[98:101], v[160:163], v[184:187], v[98:101]
	v_mfma_f32_16x16x32_bf16 v[94:97], v[168:171], v[184:187], v[94:97]
	v_mfma_f32_16x16x32_bf16 v[82:85], v[160:163], v[192:195], v[82:85]
	v_mfma_f32_16x16x32_bf16 v[78:81], v[168:171], v[192:195], v[78:81]
	v_mfma_f32_16x16x32_bf16 v[70:73], v[160:163], v[210:213], v[70:73]
	v_mfma_f32_16x16x32_bf16 v[66:69], v[168:171], v[210:213], v[66:69]
	s_barrier
	s_add_i32 s20, s80, s42
	v_lshl_add_u64 v[196:197], s[30:31], 0, v[0:1]
	s_mov_b32 m0, s20
	ds_read_b128 v[172:175], v155 offset:16384
	ds_read_b128 v[176:179], v155 offset:17408
	ds_read_b128 v[180:183], v155 offset:18432
	ds_read_b128 v[184:187], v155 offset:19456
	ds_read_b128 v[188:191], v155 offset:20480
	ds_read_b128 v[192:195], v155 offset:21504
	ds_read_b128 v[206:209], v155 offset:22528
	ds_read_b128 v[210:213], v155 offset:23552
	global_load_lds_dwordx4 v[196:197], off
	s_add_i32 m0, s20, 0x2000
	s_add_u32 s20, s30, 0x40000
	v_lshl_add_u64 v[214:215], s[30:31], 0, v[142:143]
	s_addc_u32 s21, s31, 0
	s_add_i32 s80, s81, s42
	global_load_lds_dwordx4 v[214:215], off
	v_lshl_add_u64 v[216:217], s[20:21], 0, v[0:1]
	s_mov_b32 m0, s80
	v_lshl_add_u64 v[218:219], s[34:35], 0, v[142:143]
	global_load_lds_dwordx4 v[216:217], off
	s_add_i32 m0, s80, 0x2000
	v_lshl_add_u64 v[216:217], s[20:21], 0, v[142:143]
	global_load_lds_dwordx4 v[216:217], off
	s_mov_b32 m0, s43
	v_lshl_add_u64 v[216:217], s[34:35], 0, v[0:1]
	global_load_lds_dwordx4 v[216:217], off
	s_mov_b32 m0, s46
	s_nop 0
	global_load_lds_dwordx4 v[218:219], off
	s_waitcnt vmcnt(8)
	s_waitcnt lgkmcnt(0)
	s_barrier
; #define PG8_STAGE(bufoff, gbase, voff) do { _Pragma("unroll") for (int _i = 0; _i < 2; ++_i) \
;         __builtin_amdgcn_global_load_lds((const unsigned*)((const char*)(gbase) + (voff)[_i]), (PG8_LAS unsigned*)(lds + (bufoff) + ldsw + _i * 8192), 16, 0, 0); } while (0)
; #define PG8_LDA(dst, b, h) do { _Pragma("unroll") for (int m = 0; m < 4; ++m) _Pragma("unroll") for (int k = 0; k < 2; ++k) dst[m][k] = *(const PG8_LAS bf16x8*)(lds + PG8_SA(b, h) + aoff + m * 2048 + k * 1024); } while (0)
; #define PG8_LDB(dst, b, h) do { _Pragma("unroll") for (int n = 0; n < 2; ++n) _Pragma("unroll") for (int k = 0; k < 2; ++k) dst[n][k] = *(const PG8_LAS bf16x8*)(lds + PG8_SB(b, h) + boff + n * 2048 + k * 1024); } while (0)
; #define PG8_MMA(ai, bj, At, Bt) do { __builtin_amdgcn_s_setprio(1); _Pragma("unroll") for (int m = 0; m < 4; ++m) _Pragma("unroll") for (int n = 0; n < 2; ++n) _Pragma("unroll") for (int k = 0; k < 2; ++k) \
;         acc[ai][bj][m][n] = __builtin_amdgcn_mfma_f32_16x16x32_bf16(Bt[n][k], At[m][k], acc[ai][bj][m][n], 0, 0, 0); __builtin_amdgcn_s_setprio(0); } while (0)
; #define PG8_WAIT_V(n) asm volatile("s_waitcnt vmcnt(" #n ")" ::: "memory")
; #define PG8_WAIT_L(n) asm volatile("s_waitcnt lgkmcnt(" #n ")" ::: "memory")
; #define PG8_BAR __builtin_amdgcn_s_barrier()
; #define PG8_SCHED __builtin_amdgcn_sched_barrier(0)
; template <class Epi, class Sched, bool ALIGN_EPI = false, bool SP2 = false>
; __device__ __forceinline__ void gemm_phase(PG8_LAS unsigned char* lds, const Gemm g, const Sched& S, const Epi& E) {
;     ...
;             PG8_WAIT_V(8); PG8_WAIT_L(0); PG8_BAR; PG8_MMA(1, 0, At, B0); PG8_MMA(1, 1, At, B1); PG8_BAR; PG8_SCHED;
;             PG8_LDB(B0, 1, 0); PG8_LDB(B1, 1, 1); PG8_SCHED; PG8_LDA(At, 1, 0); PG8_STAGE(PG8_SA(0, 1), a2 + hstep, voffA);
;             PG8_WAIT_V(8); PG8_WAIT_L(0); PG8_BAR; PG8_MMA(0, 0, At, B0); PG8_MMA(0, 1, At, B1); PG8_BAR; PG8_SCHED;
	v_mfma_f32_16x16x32_bf16 v[62:65], v[130:133], v[172:175], v[62:65]
	v_mfma_f32_16x16x32_bf16 v[58:61], v[138:141], v[172:175], v[58:61]
	v_mfma_f32_16x16x32_bf16 v[54:57], v[130:133], v[180:183], v[54:57]
	v_mfma_f32_16x16x32_bf16 v[42:45], v[138:141], v[180:183], v[42:45]
	v_mfma_f32_16x16x32_bf16 v[38:41], v[130:133], v[188:191], v[38:41]
	v_mfma_f32_16x16x32_bf16 v[26:29], v[138:141], v[188:191], v[26:29]
	v_mfma_f32_16x16x32_bf16 v[18:21], v[130:133], v[206:209], v[18:21]
	v_mfma_f32_16x16x32_bf16 v[10:13], v[138:141], v[206:209], v[10:13]
	v_mfma_f32_16x16x32_bf16 v[62:65], v[134:137], v[176:179], v[62:65]
	v_mfma_f32_16x16x32_bf16 v[58:61], v[148:151], v[176:179], v[58:61]
	v_mfma_f32_16x16x32_bf16 v[54:57], v[134:137], v[184:187], v[54:57]
	v_mfma_f32_16x16x32_bf16 v[42:45], v[148:151], v[184:187], v[42:45]
	v_mfma_f32_16x16x32_bf16 v[38:41], v[134:137], v[192:195], v[38:41]
	v_mfma_f32_16x16x32_bf16 v[26:29], v[148:151], v[192:195], v[26:29]
	v_mfma_f32_16x16x32_bf16 v[18:21], v[134:137], v[210:213], v[18:21]
	v_mfma_f32_16x16x32_bf16 v[10:13], v[148:151], v[210:213], v[10:13]
	v_mfma_f32_16x16x32_bf16 v[50:53], v[156:159], v[172:175], v[50:53]
	v_mfma_f32_16x16x32_bf16 v[46:49], v[164:167], v[172:175], v[46:49]
	v_mfma_f32_16x16x32_bf16 v[34:37], v[156:159], v[180:183], v[34:37]
	v_mfma_f32_16x16x32_bf16 v[30:33], v[164:167], v[180:183], v[30:33]
	v_mfma_f32_16x16x32_bf16 v[22:25], v[156:159], v[188:191], v[22:25]
	v_mfma_f32_16x16x32_bf16 v[14:17], v[164:167], v[188:191], v[14:17]
	v_mfma_f32_16x16x32_bf16 v[6:9], v[156:159], v[206:209], v[6:9]
	v_mfma_f32_16x16x32_bf16 v[2:5], v[164:167], v[206:209], v[2:5]
	v_mfma_f32_16x16x32_bf16 v[50:53], v[160:163], v[176:179], v[50:53]
	v_mfma_f32_16x16x32_bf16 v[46:49], v[168:171], v[176:179], v[46:49]
	v_mfma_f32_16x16x32_bf16 v[34:37], v[160:163], v[184:187], v[34:37]
	v_mfma_f32_16x16x32_bf16 v[30:33], v[168:171], v[184:187], v[30:33]
	v_mfma_f32_16x16x32_bf16 v[22:25], v[160:163], v[192:195], v[22:25]
	v_mfma_f32_16x16x32_bf16 v[14:17], v[168:171], v[192:195], v[14:17]
	v_mfma_f32_16x16x32_bf16 v[6:9], v[160:163], v[210:213], v[6:9]
	v_mfma_f32_16x16x32_bf16 v[2:5], v[168:171], v[210:213], v[2:5]
	s_barrier
	s_add_i32 s80, 0, 0x18000
	s_add_i32 s81, 0, 0x1c000
	v_add_u32_e32 v148, s80, v153
	v_add_u32_e32 v168, s81, v153
	ds_read_b128 v[130:133], v148
	ds_read_b128 v[134:137], v148 offset:1024
	ds_read_b128 v[138:141], v148 offset:2048
	ds_read_b128 v[148:151], v148 offset:3072
	ds_read_b128 v[156:159], v168
	ds_read_b128 v[160:163], v168 offset:1024
	ds_read_b128 v[164:167], v168 offset:2048
	ds_read_b128 v[168:171], v168 offset:3072
	s_add_u32 s20, s34, 0x40000
	s_addc_u32 s21, s35, 0
	s_mov_b32 m0, s47
	v_lshl_add_u64 v[220:221], s[20:21], 0, v[0:1]
	ds_read_b128 v[172:175], v155 offset:32768
	ds_read_b128 v[176:179], v155 offset:33792
	ds_read_b128 v[180:183], v155 offset:34816
	ds_read_b128 v[184:187], v155 offset:35840
	ds_read_b128 v[188:191], v155 offset:36864
	ds_read_b128 v[192:195], v155 offset:37888
	ds_read_b128 v[206:209], v155 offset:38912
	ds_read_b128 v[210:213], v155 offset:39936
	global_load_lds_dwordx4 v[220:221], off
	s_mov_b32 m0, s52
	v_lshl_add_u64 v[220:221], s[20:21], 0, v[142:143]
	global_load_lds_dwordx4 v[220:221], off
	s_waitcnt vmcnt(8)
	s_waitcnt lgkmcnt(0)
	s_barrier
	v_mfma_f32_16x16x32_bf16 v[126:129], v[130:133], v[172:175], v[126:129]
	v_mfma_f32_16x16x32_bf16 v[122:125], v[138:141], v[172:175], v[122:125]
	v_mfma_f32_16x16x32_bf16 v[118:121], v[130:133], v[180:183], v[118:121]
	v_mfma_f32_16x16x32_bf16 v[106:109], v[138:141], v[180:183], v[106:109]
	v_mfma_f32_16x16x32_bf16 v[102:105], v[130:133], v[188:191], v[102:105]
	v_mfma_f32_16x16x32_bf16 v[90:93], v[138:141], v[188:191], v[90:93]
	v_mfma_f32_16x16x32_bf16 v[86:89], v[130:133], v[206:209], v[86:89]
	v_mfma_f32_16x16x32_bf16 v[74:77], v[138:141], v[206:209], v[74:77]
	v_mfma_f32_16x16x32_bf16 v[126:129], v[134:137], v[176:179], v[126:129]
	v_mfma_f32_16x16x32_bf16 v[122:125], v[148:151], v[176:179], v[122:125]
	v_mfma_f32_16x16x32_bf16 v[118:121], v[134:137], v[184:187], v[118:121]
	v_mfma_f32_16x16x32_bf16 v[106:109], v[148:151], v[184:187], v[106:109]
	v_mfma_f32_16x16x32_bf16 v[102:105], v[134:137], v[192:195], v[102:105]
	v_mfma_f32_16x16x32_bf16 v[90:93], v[148:151], v[192:195], v[90:93]
	v_mfma_f32_16x16x32_bf16 v[86:89], v[134:137], v[210:213], v[86:89]
	v_mfma_f32_16x16x32_bf16 v[74:77], v[148:151], v[210:213], v[74:77]
	v_mfma_f32_16x16x32_bf16 v[114:117], v[156:159], v[172:175], v[114:117]
	v_mfma_f32_16x16x32_bf16 v[110:113], v[164:167], v[172:175], v[110:113]
	v_mfma_f32_16x16x32_bf16 v[98:101], v[156:159], v[180:183], v[98:101]
	v_mfma_f32_16x16x32_bf16 v[94:97], v[164:167], v[180:183], v[94:97]
	v_mfma_f32_16x16x32_bf16 v[82:85], v[156:159], v[188:191], v[82:85]
	v_mfma_f32_16x16x32_bf16 v[78:81], v[164:167], v[188:191], v[78:81]
	v_mfma_f32_16x16x32_bf16 v[70:73], v[156:159], v[206:209], v[70:73]
	v_mfma_f32_16x16x32_bf16 v[66:69], v[164:167], v[206:209], v[66:69]
	v_mfma_f32_16x16x32_bf16 v[114:117], v[160:163], v[176:179], v[114:117]
	v_mfma_f32_16x16x32_bf16 v[110:113], v[168:171], v[176:179], v[110:113]
	v_mfma_f32_16x16x32_bf16 v[98:101], v[160:163], v[184:187], v[98:101]
	v_mfma_f32_16x16x32_bf16 v[94:97], v[168:171], v[184:187], v[94:97]
	v_mfma_f32_16x16x32_bf16 v[82:85], v[160:163], v[192:195], v[82:85]
	v_mfma_f32_16x16x32_bf16 v[78:81], v[168:171], v[192:195], v[78:81]
	v_mfma_f32_16x16x32_bf16 v[70:73], v[160:163], v[210:213], v[70:73]
	v_mfma_f32_16x16x32_bf16 v[66:69], v[168:171], v[210:213], v[66:69]
	s_barrier
; #define PG8_STAGE(bufoff, gbase, voff) do { _Pragma("unroll") for (int _i = 0; _i < 2; ++_i) \
;         __builtin_amdgcn_global_load_lds((const unsigned*)((const char*)(gbase) + (voff)[_i]), (PG8_LAS unsigned*)(lds + (bufoff) + ldsw + _i * 8192), 16, 0, 0); } while (0)
; #define PG8_LDA(dst, b, h) do { _Pragma("unroll") for (int m = 0; m < 4; ++m) _Pragma("unroll") for (int k = 0; k < 2; ++k) dst[m][k] = *(const PG8_LAS bf16x8*)(lds + PG8_SA(b, h) + aoff + m * 2048 + k * 1024); } while (0)
; #define PG8_MMA(ai, bj, At, Bt) do { __builtin_amdgcn_s_setprio(1); _Pragma("unroll") for (int m = 0; m < 4; ++m) _Pragma("unroll") for (int n = 0; n < 2; ++n) _Pragma("unroll") for (int k = 0; k < 2; ++k) \
;         acc[ai][bj][m][n] = __builtin_amdgcn_mfma_f32_16x16x32_bf16(Bt[n][k], At[m][k], acc[ai][bj][m][n], 0, 0, 0); __builtin_amdgcn_s_setprio(0); } while (0)
; #define PG8_WAIT_V(n) asm volatile("s_waitcnt vmcnt(" #n ")" ::: "memory")
; #define PG8_WAIT_L(n) asm volatile("s_waitcnt lgkmcnt(" #n ")" ::: "memory")
; #define PG8_BAR __builtin_amdgcn_s_barrier()
; #define PG8_SCHED __builtin_amdgcn_sched_barrier(0)
; template <class Epi, class Sched, bool ALIGN_EPI = false, bool SP2 = false>
; __device__ __forceinline__ void gemm_phase(PG8_LAS unsigned char* lds, const Gemm g, const Sched& S, const Epi& E) {
;     ...
;             PG8_LDA(At, 1, 1); PG8_STAGE(PG8_SB(1, 0), b3, voffB); PG8_STAGE(PG8_SB(1, 1), b3 + hstep, voffB); PG8_STAGE(PG8_SA(1, 0), a3, voffA);
;             PG8_WAIT_V(8); PG8_WAIT_L(0); PG8_BAR; PG8_MMA(1, 0, At, B0); PG8_MMA(1, 1, At, B1); PG8_BAR; PG8_SCHED;
	s_add_i32 s20, s80, s42
	v_lshl_add_u64 v[196:197], v[196:197], 0, s[24:25]
	s_mov_b32 m0, s20
	ds_read_b128 v[172:175], v155 offset:49152
	ds_read_b128 v[176:179], v155 offset:50176
	ds_read_b128 v[180:183], v155 offset:51200
	ds_read_b128 v[184:187], v155 offset:52224
	ds_read_b128 v[188:191], v155 offset:53248
	ds_read_b128 v[192:195], v155 offset:54272
	ds_read_b128 v[206:209], v155 offset:55296
	ds_read_b128 v[210:213], v155 offset:56320
	global_load_lds_dwordx4 v[196:197], off
	s_add_i32 m0, s20, 0x2000
	s_add_u32 s20, s30, 0x40080
	v_lshl_add_u64 v[196:197], v[214:215], 0, s[24:25]
	s_addc_u32 s21, s31, 0
	s_add_i32 s30, s81, s42
	global_load_lds_dwordx4 v[196:197], off
	s_mov_b32 m0, s30
	v_lshl_add_u64 v[196:197], s[20:21], 0, v[0:1]
	global_load_lds_dwordx4 v[196:197], off
	s_add_i32 m0, s30, 0x2000
	v_lshl_add_u64 v[196:197], s[20:21], 0, v[142:143]
	global_load_lds_dwordx4 v[196:197], off
	s_mov_b32 m0, s53
	v_lshl_add_u64 v[196:197], v[216:217], 0, s[24:25]
	global_load_lds_dwordx4 v[196:197], off
	s_mov_b32 m0, s55
	v_lshl_add_u64 v[196:197], v[218:219], 0, s[24:25]
	global_load_lds_dwordx4 v[196:197], off
	s_waitcnt vmcnt(8)
	s_waitcnt lgkmcnt(0)
	s_barrier
	v_mfma_f32_16x16x32_bf16 v[62:65], v[130:133], v[172:175], v[62:65]
	v_mfma_f32_16x16x32_bf16 v[58:61], v[138:141], v[172:175], v[58:61]
	v_mfma_f32_16x16x32_bf16 v[54:57], v[130:133], v[180:183], v[54:57]
	v_mfma_f32_16x16x32_bf16 v[42:45], v[138:141], v[180:183], v[42:45]
	v_mfma_f32_16x16x32_bf16 v[38:41], v[130:133], v[188:191], v[38:41]
	v_mfma_f32_16x16x32_bf16 v[26:29], v[138:141], v[188:191], v[26:29]
	v_mfma_f32_16x16x32_bf16 v[18:21], v[130:133], v[206:209], v[18:21]
	v_mfma_f32_16x16x32_bf16 v[10:13], v[138:141], v[206:209], v[10:13]
	v_mfma_f32_16x16x32_bf16 v[62:65], v[134:137], v[176:179], v[62:65]
	v_mfma_f32_16x16x32_bf16 v[58:61], v[148:151], v[176:179], v[58:61]
	v_mfma_f32_16x16x32_bf16 v[54:57], v[134:137], v[184:187], v[54:57]
	v_mfma_f32_16x16x32_bf16 v[42:45], v[148:151], v[184:187], v[42:45]
	v_mfma_f32_16x16x32_bf16 v[38:41], v[134:137], v[192:195], v[38:41]
	v_mfma_f32_16x16x32_bf16 v[26:29], v[148:151], v[192:195], v[26:29]
	v_mfma_f32_16x16x32_bf16 v[18:21], v[134:137], v[210:213], v[18:21]
	v_mfma_f32_16x16x32_bf16 v[10:13], v[148:151], v[210:213], v[10:13]
	v_mfma_f32_16x16x32_bf16 v[50:53], v[156:159], v[172:175], v[50:53]
	v_mfma_f32_16x16x32_bf16 v[46:49], v[164:167], v[172:175], v[46:49]
	v_mfma_f32_16x16x32_bf16 v[34:37], v[156:159], v[180:183], v[34:37]
	v_mfma_f32_16x16x32_bf16 v[30:33], v[164:167], v[180:183], v[30:33]
	v_mfma_f32_16x16x32_bf16 v[22:25], v[156:159], v[188:191], v[22:25]
	v_mfma_f32_16x16x32_bf16 v[14:17], v[164:167], v[188:191], v[14:17]
	v_mfma_f32_16x16x32_bf16 v[6:9], v[156:159], v[206:209], v[6:9]
	v_mfma_f32_16x16x32_bf16 v[2:5], v[164:167], v[206:209], v[2:5]
	v_mfma_f32_16x16x32_bf16 v[50:53], v[160:163], v[176:179], v[50:53]
	v_mfma_f32_16x16x32_bf16 v[46:49], v[168:171], v[176:179], v[46:49]
	v_mfma_f32_16x16x32_bf16 v[34:37], v[160:163], v[184:187], v[34:37]
	v_mfma_f32_16x16x32_bf16 v[30:33], v[168:171], v[184:187], v[30:33]
	v_mfma_f32_16x16x32_bf16 v[22:25], v[160:163], v[192:195], v[22:25]
	v_mfma_f32_16x16x32_bf16 v[14:17], v[168:171], v[192:195], v[14:17]
	v_mfma_f32_16x16x32_bf16 v[6:9], v[160:163], v[210:213], v[6:9]
	v_mfma_f32_16x16x32_bf16 v[2:5], v[168:171], v[210:213], v[2:5]
	s_barrier
	s_add_i32 s73, s73, 2
	s_add_u32 s8, s8, 0x100
	s_addc_u32 s9, s9, 0
	s_add_u32 s58, s58, 0x100
	s_addc_u32 s72, s72, 0
	s_cmp_gt_u32 s73, 13
	s_cbranch_scc0 .LBB0_351
	s_and_b64 vcc, exec, s[10:11]
	s_cbranch_vccz .LBB0_354
	s_barrier
